# v54 + RG-LRU out-proj weight conversion staggered into phase 1; p->bf16 loop issues all loads up front
# baseline (speedup 1.0000x reference)
; #define LAS __attribute__((address_space(3)))
; __device__ __forceinline__ void xpose_item(const float* src, int ld, bf16_t* dst, int K, int k0, LAS float* scr, int lane, const float* gk) {
;     if (src) {
; #pragma unroll 8
;         for (int i = 0; i < 32; ++i) { const int kk = 2 * i + (lane >> 5); scr[kk * 33 + (lane & 31)] = __builtin_nontemporal_load(src + (size_t)(k0 + kk) * ld + (lane & 31)); }
; __device__ __forceinline__ int xpose_all(const float* src, const float* src2, int ld, int K, int ndst, int nsrc, int mode, bf16_t* dst, int it, int NGW, LAS float* scr, int lane, const float* gvec = nullptr) {
;     const int nblk = ndst / 32, nitems = (K / 64) * nblk;
;     for (; it < nitems; it += NGW) {
;         const int kb = it / nblk, nb = it % nblk, n0 = nb * 32; const float* sp;
;         if (mode == 0) sp = (n0 < nsrc) ? src + n0 : nullptr;
;         else if (mode == 1) { const int unit = n0 >> 8, bj = (n0 >> 7) & 1, cl = n0 & 127; sp = (bj ? src2 : src) + unit * 128 + cl; }
;         else if (mode == 3) { const int pn = n0 >> 8, cl = n0 & 255; sp = src + ((pn >> 2) & 1) * 2048 + ((pn & 3) + 4 * (pn >> 3)) * 256 + cl; }
;         else { const int unit = n0 >> 8, bj = (n0 >> 7) & 1, cl = n0 & 127; sp = (bj ? src2 : src) + (size_t)(unit >> 1) * 65536 + (unit & 1) * 128 + cl; }
;         xpose_item(sp, ld, dst + (size_t)n0 * K, K, kb * 64, scr, lane, gvec);
.Lxpg0p1e_end:
	s_sub_i32 s59, s59, 0x2c00
	s_cmpk_ge_i32 s59, 0x800
	s_cbranch_scc1 .Lxpwap1e_end
	s_load_dwordx2 s[60:61], s[92:93], 0x70
	s_load_dwordx2 s[62:63], s[92:93], 0xe8
	v_mov_b32_e32 v5, 0x2000
	v_mul_u32_u24_e32 v5, v3, v5
	v_add_u32_e32 v5, v5, v4
	v_mov_b32_e32 v10, 0x1000
	v_mul_u32_u24_e32 v10, v8, v10
	v_lshl_add_u32 v12, v7, 4, v10
	v_add_u32_e32 v13, 0x8000, v12
	v_add_u32_e32 v14, 0x10000, v12
	v_add_u32_e32 v15, 0x18000, v12
	s_waitcnt lgkmcnt(0)
	s_add_u32 s62, s62, 0x1200000
	s_addc_u32 s63, s63, 0
	s_lshr_b32 s64, s59, 6
	s_and_b32 s65, s59, 63
	s_mul_i32 s66, s64, 0x80000
	s_lshl_b32 s67, s65, 7
	s_add_i32 s66, s66, s67
	s_add_u32 s66, s60, s66
	s_addc_u32 s67, s61, 0
	v_mov_b32_e32 v11, v5
	global_load_dword v20, v11, s[66:67] nt
	v_add_u32_e32 v11, 0x4000, v11
	global_load_dword v21, v11, s[66:67] nt
	v_add_u32_e32 v11, 0x4000, v11
	global_load_dword v22, v11, s[66:67] nt
	v_add_u32_e32 v11, 0x4000, v11
	global_load_dword v23, v11, s[66:67] nt
	v_add_u32_e32 v11, 0x4000, v11
	global_load_dword v24, v11, s[66:67] nt
	v_add_u32_e32 v11, 0x4000, v11
	global_load_dword v25, v11, s[66:67] nt
	v_add_u32_e32 v11, 0x4000, v11
	global_load_dword v26, v11, s[66:67] nt
	v_add_u32_e32 v11, 0x4000, v11
	global_load_dword v27, v11, s[66:67] nt
	v_add_u32_e32 v11, 0x4000, v11
	global_load_dword v28, v11, s[66:67] nt
	v_add_u32_e32 v11, 0x4000, v11
	global_load_dword v29, v11, s[66:67] nt
	v_add_u32_e32 v11, 0x4000, v11
	global_load_dword v30, v11, s[66:67] nt
	v_add_u32_e32 v11, 0x4000, v11
	global_load_dword v31, v11, s[66:67] nt
	v_add_u32_e32 v11, 0x4000, v11
	global_load_dword v32, v11, s[66:67] nt
	v_add_u32_e32 v11, 0x4000, v11
	global_load_dword v33, v11, s[66:67] nt
	v_add_u32_e32 v11, 0x4000, v11
	global_load_dword v34, v11, s[66:67] nt
	v_add_u32_e32 v11, 0x4000, v11
	global_load_dword v35, v11, s[66:67] nt
	v_add_u32_e32 v11, 0x4000, v11
	global_load_dword v36, v11, s[66:67] nt
	v_add_u32_e32 v11, 0x4000, v11
	global_load_dword v37, v11, s[66:67] nt
	v_add_u32_e32 v11, 0x4000, v11
	global_load_dword v38, v11, s[66:67] nt
	v_add_u32_e32 v11, 0x4000, v11
	global_load_dword v39, v11, s[66:67] nt
	v_add_u32_e32 v11, 0x4000, v11
	global_load_dword v40, v11, s[66:67] nt
	v_add_u32_e32 v11, 0x4000, v11
	global_load_dword v41, v11, s[66:67] nt
	v_add_u32_e32 v11, 0x4000, v11
	global_load_dword v42, v11, s[66:67] nt
	v_add_u32_e32 v11, 0x4000, v11
	global_load_dword v43, v11, s[66:67] nt
	v_add_u32_e32 v11, 0x4000, v11
	global_load_dword v44, v11, s[66:67] nt
	v_add_u32_e32 v11, 0x4000, v11
	global_load_dword v45, v11, s[66:67] nt
	v_add_u32_e32 v11, 0x4000, v11
	global_load_dword v46, v11, s[66:67] nt
	v_add_u32_e32 v11, 0x4000, v11
	global_load_dword v47, v11, s[66:67] nt
	v_add_u32_e32 v11, 0x4000, v11
	global_load_dword v48, v11, s[66:67] nt
	v_add_u32_e32 v11, 0x4000, v11
	global_load_dword v49, v11, s[66:67] nt
	v_add_u32_e32 v11, 0x4000, v11
	global_load_dword v50, v11, s[66:67] nt
	v_add_u32_e32 v11, 0x4000, v11
	global_load_dword v51, v11, s[66:67] nt
.Lxpwap1e_loop:
	s_add_i32 s32, s59, 0x800
	s_cmpk_lt_i32 s32, 0x800
	s_cbranch_scc0 .Lxpwap1e_dumB
	s_lshr_b32 s64, s32, 6
	s_and_b32 s65, s32, 63
	s_mul_i32 s66, s64, 0x80000
	s_lshl_b32 s67, s65, 7
	s_add_i32 s66, s66, s67
	s_add_u32 s66, s60, s66
	s_addc_u32 s67, s61, 0
	v_mov_b32_e32 v11, v5
	global_load_dword v108, v11, s[66:67] nt
	v_add_u32_e32 v11, 0x4000, v11
	global_load_dword v109, v11, s[66:67] nt
	v_add_u32_e32 v11, 0x4000, v11
	global_load_dword v110, v11, s[66:67] nt
	v_add_u32_e32 v11, 0x4000, v11
	global_load_dword v111, v11, s[66:67] nt
	v_add_u32_e32 v11, 0x4000, v11
	global_load_dword v112, v11, s[66:67] nt
	v_add_u32_e32 v11, 0x4000, v11
	global_load_dword v113, v11, s[66:67] nt
	v_add_u32_e32 v11, 0x4000, v11
	global_load_dword v114, v11, s[66:67] nt
	v_add_u32_e32 v11, 0x4000, v11
	global_load_dword v115, v11, s[66:67] nt
	v_add_u32_e32 v11, 0x4000, v11
	global_load_dword v116, v11, s[66:67] nt
	v_add_u32_e32 v11, 0x4000, v11
	global_load_dword v117, v11, s[66:67] nt
	v_add_u32_e32 v11, 0x4000, v11
	global_load_dword v118, v11, s[66:67] nt
	v_add_u32_e32 v11, 0x4000, v11
	global_load_dword v119, v11, s[66:67] nt
	v_add_u32_e32 v11, 0x4000, v11
	global_load_dword v120, v11, s[66:67] nt
	v_add_u32_e32 v11, 0x4000, v11
	global_load_dword v121, v11, s[66:67] nt
	v_add_u32_e32 v11, 0x4000, v11
	global_load_dword v122, v11, s[66:67] nt
	v_add_u32_e32 v11, 0x4000, v11
	global_load_dword v123, v11, s[66:67] nt
	v_add_u32_e32 v11, 0x4000, v11
	global_load_dword v124, v11, s[66:67] nt
	v_add_u32_e32 v11, 0x4000, v11
	global_load_dword v125, v11, s[66:67] nt
	v_add_u32_e32 v11, 0x4000, v11
	global_load_dword v126, v11, s[66:67] nt
	v_add_u32_e32 v11, 0x4000, v11
	global_load_dword v127, v11, s[66:67] nt
	v_add_u32_e32 v11, 0x4000, v11
	global_load_dword v128, v11, s[66:67] nt
	v_add_u32_e32 v11, 0x4000, v11
	global_load_dword v129, v11, s[66:67] nt
	v_add_u32_e32 v11, 0x4000, v11
	global_load_dword v130, v11, s[66:67] nt
	v_add_u32_e32 v11, 0x4000, v11
	global_load_dword v131, v11, s[66:67] nt
	v_add_u32_e32 v11, 0x4000, v11
	global_load_dword v132, v11, s[66:67] nt
	v_add_u32_e32 v11, 0x4000, v11
	global_load_dword v133, v11, s[66:67] nt
	v_add_u32_e32 v11, 0x4000, v11
	global_load_dword v134, v11, s[66:67] nt
	v_add_u32_e32 v11, 0x4000, v11
	global_load_dword v135, v11, s[66:67] nt
	v_add_u32_e32 v11, 0x4000, v11
	global_load_dword v136, v11, s[66:67] nt
	v_add_u32_e32 v11, 0x4000, v11
	global_load_dword v137, v11, s[66:67] nt
	v_add_u32_e32 v11, 0x4000, v11
	global_load_dword v138, v11, s[66:67] nt
	v_add_u32_e32 v11, 0x4000, v11
	global_load_dword v139, v11, s[66:67] nt
	s_branch .Lxpwap1e_procA

; #define LAS __attribute__((address_space(3)))
; __device__ __forceinline__ unsigned cvt_pk_bf16(float lo, float hi) { unsigned r; asm volatile("v_cvt_pk_bf16_f32 %0, %1, %2" : "=v"(r) : "v"(lo), "v"(hi)); return r; }
; __device__ __forceinline__ void xpose_item(const float* src, int ld, bf16_t* dst, int K, int k0, LAS float* scr, int lane, const float* gk) {
;     ...
;         for (int i = 0; i < 32; ++i) { const int kk = 2 * i + (lane >> 5); scr[kk * 33 + (lane & 31)] = __builtin_nontemporal_load(src + (size_t)(k0 + kk) * ld + (lane & 31)); }
;     } else {
; #pragma unroll 8
;         for (int i = 0; i < 32; ++i) { const int kk = 2 * i + (lane >> 5); scr[kk * 33 + (lane & 31)] = 0.f; }
;     }
;     const int c = lane & 7;
;     f32x4 g0 = (f32x4){1.f, 1.f, 1.f, 1.f}, g1 = g0;
;     if (gk) { g0 = *(const f32x4*)(gk + k0 + 8 * c); g1 = *(const f32x4*)(gk + k0 + 8 * c + 4); }
;     asm volatile("s_waitcnt lgkmcnt(0)" ::: "memory");
; #pragma unroll
;     for (int j = 0; j < 4; ++j) { const int n = (lane >> 3) + 8 * j; const LAS float* s = scr + (8 * c) * 33 + n;
;         u32x4 o; o.x = cvt_pk_bf16(s[0 * 33] * g0[0], s[1 * 33] * g0[1]); o.y = cvt_pk_bf16(s[2 * 33] * g0[2], s[3 * 33] * g0[3]); o.z = cvt_pk_bf16(s[4 * 33] * g1[0], s[5 * 33] * g1[1]); o.w = cvt_pk_bf16(s[6 * 33] * g1[2], s[7 * 33] * g1[3]);
;         *(u32x4*)(dst + (size_t)n * K + k0 + 8 * c) = o; }
.Lxpwap1e_procA:
	s_lshr_b32 s64, s59, 6
	s_and_b32 s65, s59, 63
	s_mul_i32 s68, s65, 0x20000
	s_lshl_b32 s64, s64, 7
	s_add_i32 s68, s68, s64
	s_add_u32 s64, s62, s68
	s_addc_u32 s65, s63, 0
	s_waitcnt vmcnt(63)
	ds_write_b32 v6, v20 offset:0
	s_waitcnt vmcnt(62)
	ds_write_b32 v6, v21 offset:264
	s_waitcnt vmcnt(61)
	ds_write_b32 v6, v22 offset:528
	s_waitcnt vmcnt(60)
	ds_write_b32 v6, v23 offset:792
	s_waitcnt vmcnt(59)
	ds_write_b32 v6, v24 offset:1056
	s_waitcnt vmcnt(58)
	ds_write_b32 v6, v25 offset:1320
	s_waitcnt vmcnt(57)
	ds_write_b32 v6, v26 offset:1584
	s_waitcnt vmcnt(56)
	ds_write_b32 v6, v27 offset:1848
	s_waitcnt vmcnt(55)
	ds_write_b32 v6, v28 offset:2112
	s_waitcnt vmcnt(54)
	ds_write_b32 v6, v29 offset:2376
	s_waitcnt vmcnt(53)
	ds_write_b32 v6, v30 offset:2640
	s_waitcnt vmcnt(52)
	ds_write_b32 v6, v31 offset:2904
	s_waitcnt vmcnt(51)
	ds_write_b32 v6, v32 offset:3168
	s_waitcnt vmcnt(50)
	ds_write_b32 v6, v33 offset:3432
	s_waitcnt vmcnt(49)
	ds_write_b32 v6, v34 offset:3696
	s_waitcnt vmcnt(48)
	ds_write_b32 v6, v35 offset:3960
	s_waitcnt vmcnt(47)
	ds_write_b32 v6, v36 offset:4224
	s_waitcnt vmcnt(46)
	ds_write_b32 v6, v37 offset:4488
	s_waitcnt vmcnt(45)
	ds_write_b32 v6, v38 offset:4752
	s_waitcnt vmcnt(44)
	ds_write_b32 v6, v39 offset:5016
	s_waitcnt vmcnt(43)
	ds_write_b32 v6, v40 offset:5280
	s_waitcnt vmcnt(42)
	ds_write_b32 v6, v41 offset:5544
	s_waitcnt vmcnt(41)
	ds_write_b32 v6, v42 offset:5808
	s_waitcnt vmcnt(40)
	ds_write_b32 v6, v43 offset:6072
	s_waitcnt vmcnt(39)
	ds_write_b32 v6, v44 offset:6336
	s_waitcnt vmcnt(38)
	ds_write_b32 v6, v45 offset:6600
	s_waitcnt vmcnt(37)
	ds_write_b32 v6, v46 offset:6864
	s_waitcnt vmcnt(36)
	ds_write_b32 v6, v47 offset:7128
	s_waitcnt vmcnt(35)
	ds_write_b32 v6, v48 offset:7392
	s_waitcnt vmcnt(34)
	ds_write_b32 v6, v49 offset:7656
	s_waitcnt vmcnt(33)
	ds_write_b32 v6, v50 offset:7920
	s_waitcnt vmcnt(32)
	ds_write_b32 v6, v51 offset:8184
	s_waitcnt lgkmcnt(0)
	ds_read2_b32 v[60:61], v9 offset0:0 offset1:33
	ds_read2_b32 v[62:63], v9 offset0:66 offset1:99
	ds_read2_b32 v[64:65], v9 offset0:132 offset1:165
	ds_read2_b32 v[66:67], v9 offset0:198 offset1:231
	ds_read2_b32 v[68:69], v9 offset0:8 offset1:41
	ds_read2_b32 v[70:71], v9 offset0:74 offset1:107
	ds_read2_b32 v[72:73], v9 offset0:140 offset1:173
	ds_read2_b32 v[74:75], v9 offset0:206 offset1:239
	ds_read2_b32 v[76:77], v9 offset0:16 offset1:49
	ds_read2_b32 v[78:79], v9 offset0:82 offset1:115
	ds_read2_b32 v[80:81], v9 offset0:148 offset1:181
	ds_read2_b32 v[82:83], v9 offset0:214 offset1:247
	ds_read2_b32 v[84:85], v9 offset0:24 offset1:57
	ds_read2_b32 v[86:87], v9 offset0:90 offset1:123
	ds_read2_b32 v[88:89], v9 offset0:156 offset1:189
	ds_read2_b32 v[90:91], v9 offset0:222 offset1:255
	s_waitcnt lgkmcnt(12)
	v_cvt_pk_bf16_f32 v92, v60, v61
	v_cvt_pk_bf16_f32 v93, v62, v63
	v_cvt_pk_bf16_f32 v94, v64, v65
	v_cvt_pk_bf16_f32 v95, v66, v67
	global_store_dwordx4 v12, v[92:95], s[64:65]
	s_waitcnt lgkmcnt(8)
	v_cvt_pk_bf16_f32 v96, v68, v69
	v_cvt_pk_bf16_f32 v97, v70, v71
	v_cvt_pk_bf16_f32 v98, v72, v73
	v_cvt_pk_bf16_f32 v99, v74, v75
	global_store_dwordx4 v13, v[96:99], s[64:65]
	s_waitcnt lgkmcnt(4)
	v_cvt_pk_bf16_f32 v100, v76, v77
	v_cvt_pk_bf16_f32 v101, v78, v79
	v_cvt_pk_bf16_f32 v102, v80, v81
	v_cvt_pk_bf16_f32 v103, v82, v83
	global_store_dwordx4 v14, v[100:103], s[64:65]
	s_waitcnt lgkmcnt(0)
	v_cvt_pk_bf16_f32 v104, v84, v85
	v_cvt_pk_bf16_f32 v105, v86, v87
	v_cvt_pk_bf16_f32 v106, v88, v89
	v_cvt_pk_bf16_f32 v107, v90, v91
	global_store_dwordx4 v15, v[104:107], s[64:65]
	s_cmpk_lt_i32 s32, 0x800
	s_cbranch_scc0 .Lxpwap1e_fin
	s_add_i32 s59, s32, 0x800
	s_cmpk_lt_i32 s59, 0x800
	s_cbranch_scc0 .Lxpwap1e_dumA
	s_lshr_b32 s64, s59, 6
	s_and_b32 s65, s59, 63
	s_mul_i32 s66, s64, 0x80000
	s_lshl_b32 s67, s65, 7
	s_add_i32 s66, s66, s67
	s_add_u32 s66, s60, s66
	s_addc_u32 s67, s61, 0
	v_mov_b32_e32 v11, v5
	global_load_dword v20, v11, s[66:67] nt
	v_add_u32_e32 v11, 0x4000, v11
	global_load_dword v21, v11, s[66:67] nt
	v_add_u32_e32 v11, 0x4000, v11
	global_load_dword v22, v11, s[66:67] nt
	v_add_u32_e32 v11, 0x4000, v11
	global_load_dword v23, v11, s[66:67] nt
	v_add_u32_e32 v11, 0x4000, v11
	global_load_dword v24, v11, s[66:67] nt
	v_add_u32_e32 v11, 0x4000, v11
	global_load_dword v25, v11, s[66:67] nt
	v_add_u32_e32 v11, 0x4000, v11
	global_load_dword v26, v11, s[66:67] nt
	v_add_u32_e32 v11, 0x4000, v11
	global_load_dword v27, v11, s[66:67] nt
	v_add_u32_e32 v11, 0x4000, v11
	global_load_dword v28, v11, s[66:67] nt
	v_add_u32_e32 v11, 0x4000, v11
	global_load_dword v29, v11, s[66:67] nt
	v_add_u32_e32 v11, 0x4000, v11
	global_load_dword v30, v11, s[66:67] nt
	v_add_u32_e32 v11, 0x4000, v11
	global_load_dword v31, v11, s[66:67] nt
	v_add_u32_e32 v11, 0x4000, v11
	global_load_dword v32, v11, s[66:67] nt
	v_add_u32_e32 v11, 0x4000, v11
	global_load_dword v33, v11, s[66:67] nt
	v_add_u32_e32 v11, 0x4000, v11
	global_load_dword v34, v11, s[66:67] nt
	v_add_u32_e32 v11, 0x4000, v11
	global_load_dword v35, v11, s[66:67] nt
	v_add_u32_e32 v11, 0x4000, v11
	global_load_dword v36, v11, s[66:67] nt
	v_add_u32_e32 v11, 0x4000, v11
	global_load_dword v37, v11, s[66:67] nt
	v_add_u32_e32 v11, 0x4000, v11
	global_load_dword v38, v11, s[66:67] nt
	v_add_u32_e32 v11, 0x4000, v11
	global_load_dword v39, v11, s[66:67] nt
	v_add_u32_e32 v11, 0x4000, v11
	global_load_dword v40, v11, s[66:67] nt
	v_add_u32_e32 v11, 0x4000, v11
	global_load_dword v41, v11, s[66:67] nt
	v_add_u32_e32 v11, 0x4000, v11
	global_load_dword v42, v11, s[66:67] nt
	v_add_u32_e32 v11, 0x4000, v11
	global_load_dword v43, v11, s[66:67] nt
	v_add_u32_e32 v11, 0x4000, v11
	global_load_dword v44, v11, s[66:67] nt
	v_add_u32_e32 v11, 0x4000, v11
	global_load_dword v45, v11, s[66:67] nt
	v_add_u32_e32 v11, 0x4000, v11
	global_load_dword v46, v11, s[66:67] nt
	v_add_u32_e32 v11, 0x4000, v11
	global_load_dword v47, v11, s[66:67] nt
	v_add_u32_e32 v11, 0x4000, v11
	global_load_dword v48, v11, s[66:67] nt
	v_add_u32_e32 v11, 0x4000, v11
	global_load_dword v49, v11, s[66:67] nt
	v_add_u32_e32 v11, 0x4000, v11
	global_load_dword v50, v11, s[66:67] nt
	v_add_u32_e32 v11, 0x4000, v11
	global_load_dword v51, v11, s[66:67] nt
	s_branch .Lxpwap1e_procB

; #define LAS __attribute__((address_space(3)))
; __device__ __forceinline__ unsigned cvt_pk_bf16(float lo, float hi) { unsigned r; asm volatile("v_cvt_pk_bf16_f32 %0, %1, %2" : "=v"(r) : "v"(lo), "v"(hi)); return r; }
; __device__ __forceinline__ void xpose_item(const float* src, int ld, bf16_t* dst, int K, int k0, LAS float* scr, int lane, const float* gk) {
;     ...
;         for (int i = 0; i < 32; ++i) { const int kk = 2 * i + (lane >> 5); scr[kk * 33 + (lane & 31)] = __builtin_nontemporal_load(src + (size_t)(k0 + kk) * ld + (lane & 31)); }
;     } else {
; #pragma unroll 8
;         for (int i = 0; i < 32; ++i) { const int kk = 2 * i + (lane >> 5); scr[kk * 33 + (lane & 31)] = 0.f; }
;     }
;     const int c = lane & 7;
;     f32x4 g0 = (f32x4){1.f, 1.f, 1.f, 1.f}, g1 = g0;
;     if (gk) { g0 = *(const f32x4*)(gk + k0 + 8 * c); g1 = *(const f32x4*)(gk + k0 + 8 * c + 4); }
;     asm volatile("s_waitcnt lgkmcnt(0)" ::: "memory");
; #pragma unroll
;     for (int j = 0; j < 4; ++j) { const int n = (lane >> 3) + 8 * j; const LAS float* s = scr + (8 * c) * 33 + n;
;         u32x4 o; o.x = cvt_pk_bf16(s[0 * 33] * g0[0], s[1 * 33] * g0[1]); o.y = cvt_pk_bf16(s[2 * 33] * g0[2], s[3 * 33] * g0[3]); o.z = cvt_pk_bf16(s[4 * 33] * g1[0], s[5 * 33] * g1[1]); o.w = cvt_pk_bf16(s[6 * 33] * g1[2], s[7 * 33] * g1[3]);
;         *(u32x4*)(dst + (size_t)n * K + k0 + 8 * c) = o; }
.Lxpwap1e_procB:
	s_lshr_b32 s64, s32, 6
	s_and_b32 s65, s32, 63
	s_mul_i32 s68, s65, 0x20000
	s_lshl_b32 s64, s64, 7
	s_add_i32 s68, s68, s64
	s_add_u32 s64, s62, s68
	s_addc_u32 s65, s63, 0
	s_waitcnt vmcnt(63)
	ds_write_b32 v6, v108 offset:0
	s_waitcnt vmcnt(62)
	ds_write_b32 v6, v109 offset:264
	s_waitcnt vmcnt(61)
	ds_write_b32 v6, v110 offset:528
	s_waitcnt vmcnt(60)
	ds_write_b32 v6, v111 offset:792
	s_waitcnt vmcnt(59)
	ds_write_b32 v6, v112 offset:1056
	s_waitcnt vmcnt(58)
	ds_write_b32 v6, v113 offset:1320
	s_waitcnt vmcnt(57)
	ds_write_b32 v6, v114 offset:1584
	s_waitcnt vmcnt(56)
	ds_write_b32 v6, v115 offset:1848
	s_waitcnt vmcnt(55)
	ds_write_b32 v6, v116 offset:2112
	s_waitcnt vmcnt(54)
	ds_write_b32 v6, v117 offset:2376
	s_waitcnt vmcnt(53)
	ds_write_b32 v6, v118 offset:2640
	s_waitcnt vmcnt(52)
	ds_write_b32 v6, v119 offset:2904
	s_waitcnt vmcnt(51)
	ds_write_b32 v6, v120 offset:3168
	s_waitcnt vmcnt(50)
	ds_write_b32 v6, v121 offset:3432
	s_waitcnt vmcnt(49)
	ds_write_b32 v6, v122 offset:3696
	s_waitcnt vmcnt(48)
	ds_write_b32 v6, v123 offset:3960
	s_waitcnt vmcnt(47)
	ds_write_b32 v6, v124 offset:4224
	s_waitcnt vmcnt(46)
	ds_write_b32 v6, v125 offset:4488
	s_waitcnt vmcnt(45)
	ds_write_b32 v6, v126 offset:4752
	s_waitcnt vmcnt(44)
	ds_write_b32 v6, v127 offset:5016
	s_waitcnt vmcnt(43)
	ds_write_b32 v6, v128 offset:5280
	s_waitcnt vmcnt(42)
	ds_write_b32 v6, v129 offset:5544
	s_waitcnt vmcnt(41)
	ds_write_b32 v6, v130 offset:5808
	s_waitcnt vmcnt(40)
	ds_write_b32 v6, v131 offset:6072
	s_waitcnt vmcnt(39)
	ds_write_b32 v6, v132 offset:6336
	s_waitcnt vmcnt(38)
	ds_write_b32 v6, v133 offset:6600
	s_waitcnt vmcnt(37)
	ds_write_b32 v6, v134 offset:6864
	s_waitcnt vmcnt(36)
	ds_write_b32 v6, v135 offset:7128
	s_waitcnt vmcnt(35)
	ds_write_b32 v6, v136 offset:7392
	s_waitcnt vmcnt(34)
	ds_write_b32 v6, v137 offset:7656
	s_waitcnt vmcnt(33)
	ds_write_b32 v6, v138 offset:7920
	s_waitcnt vmcnt(32)
	ds_write_b32 v6, v139 offset:8184
	s_waitcnt lgkmcnt(0)
	ds_read2_b32 v[60:61], v9 offset0:0 offset1:33
	ds_read2_b32 v[62:63], v9 offset0:66 offset1:99
	ds_read2_b32 v[64:65], v9 offset0:132 offset1:165
	ds_read2_b32 v[66:67], v9 offset0:198 offset1:231
	ds_read2_b32 v[68:69], v9 offset0:8 offset1:41
	ds_read2_b32 v[70:71], v9 offset0:74 offset1:107
	ds_read2_b32 v[72:73], v9 offset0:140 offset1:173
	ds_read2_b32 v[74:75], v9 offset0:206 offset1:239
	ds_read2_b32 v[76:77], v9 offset0:16 offset1:49
	ds_read2_b32 v[78:79], v9 offset0:82 offset1:115
	ds_read2_b32 v[80:81], v9 offset0:148 offset1:181
	ds_read2_b32 v[82:83], v9 offset0:214 offset1:247
	ds_read2_b32 v[84:85], v9 offset0:24 offset1:57
	ds_read2_b32 v[86:87], v9 offset0:90 offset1:123
	ds_read2_b32 v[88:89], v9 offset0:156 offset1:189
	ds_read2_b32 v[90:91], v9 offset0:222 offset1:255
	s_waitcnt lgkmcnt(12)
	v_cvt_pk_bf16_f32 v92, v60, v61
	v_cvt_pk_bf16_f32 v93, v62, v63
	v_cvt_pk_bf16_f32 v94, v64, v65
	v_cvt_pk_bf16_f32 v95, v66, v67
	global_store_dwordx4 v12, v[92:95], s[64:65]
	s_waitcnt lgkmcnt(8)
	v_cvt_pk_bf16_f32 v96, v68, v69
	v_cvt_pk_bf16_f32 v97, v70, v71
	v_cvt_pk_bf16_f32 v98, v72, v73
	v_cvt_pk_bf16_f32 v99, v74, v75
	global_store_dwordx4 v13, v[96:99], s[64:65]
	s_waitcnt lgkmcnt(4)
	v_cvt_pk_bf16_f32 v100, v76, v77
	v_cvt_pk_bf16_f32 v101, v78, v79
	v_cvt_pk_bf16_f32 v102, v80, v81
	v_cvt_pk_bf16_f32 v103, v82, v83
	global_store_dwordx4 v14, v[100:103], s[64:65]
	s_waitcnt lgkmcnt(0)
	v_cvt_pk_bf16_f32 v104, v84, v85
	v_cvt_pk_bf16_f32 v105, v86, v87
	v_cvt_pk_bf16_f32 v106, v88, v89
	v_cvt_pk_bf16_f32 v107, v90, v91
	global_store_dwordx4 v15, v[104:107], s[64:65]
	s_cmpk_lt_i32 s59, 0x800
	s_cbranch_scc1 .Lxpwap1e_loop
	s_branch .Lxpwap1e_drain

; __device__ __forceinline__ void xpose_item(const float* src, int ld, bf16_t* dst, int K, int k0, LAS float* scr, int lane, const float* gk) {
;     ...
;     asm volatile("s_waitcnt lgkmcnt(0)" ::: "memory");
; }
.Lxpwap1e_end:
	s_sub_i32 s59, s59, 0x800
	s_movk_i32 s33, 0x84
	s_waitcnt lgkmcnt(0)
	s_barrier

; __device__ __forceinline__ void xpose_item(const float* src, int ld, bf16_t* dst, int K, int k0, LAS float* scr, int lane, const float* gk) {
;     ...
;     asm volatile("s_waitcnt lgkmcnt(0)" ::: "memory");
; }
.Lxpwap1x_end:
	s_sub_i32 s59, s59, 0x800
	s_movk_i32 s33, 0x84

; __device__ __forceinline__ int xpose_all(const float* src, const float* src2, int ld, int K, int ndst, int nsrc, int mode, bf16_t* dst, int it, int NGW, LAS float* scr, int lane, const float* gvec = nullptr) {
;     ...
;     for (; it < nitems; it += NGW) {
;         const int kb = it / nblk, nb = it % nblk, n0 = nb * 32; const float* sp;
;         if (mode == 0) sp = (n0 < nsrc) ? src + n0 : nullptr;
;         else if (mode == 1) { const int unit = n0 >> 8, bj = (n0 >> 7) & 1, cl = n0 & 127; sp = (bj ? src2 : src) + unit * 128 + cl; }
;         else if (mode == 3) { const int pn = n0 >> 8, cl = n0 & 255; sp = src + ((pn >> 2) & 1) * 2048 + ((pn & 3) + 4 * (pn >> 3)) * 256 + cl; }
;         else { const int unit = n0 >> 8, bj = (n0 >> 7) & 1, cl = n0 & 127; sp = (bj ? src2 : src) + (size_t)(unit >> 1) * 65536 + (unit & 1) * 128 + cl; }
;         xpose_item(sp, ld, dst + (size_t)n0 * K, K, kb * 64, scr, lane, gvec);
;     }
;     return it - nitems;
; __global__ void __launch_bounds__(512) mega(Args a_byval) {
;     ...
;                 it = xpose_all(a.in[9], a.in[11], 256, 256, 4096, 4096, 2, (bf16_t*)(ws + WS_W_GATE), it, NGW, scr, lane);
;                 it = xpose_all(a.in[14], nullptr, 2048, 2048, 2048, 2048, 0, (bf16_t*)(ws + WS_W_AOUT), it, NGW, scr, lane);
.LBB0_608:
	s_add_i32 s12, s14, 0xfffffe00
	v_readlane_b32 vcc_lo, v255, 5
	s_cmpk_lg_i32 vcc_lo, 0x100
	s_cbranch_scc1 .Lxs608
	s_addk_i32 s12, 0x800
	s_branch .LBB0_618
.Lxs608:
	s_cmpk_gt_u32 s12, 0x7ff
	s_cbranch_scc1 .LBB0_618
	s_load_dwordx2 s[2:3], s[92:93], 0x70
	s_waitcnt lgkmcnt(0)
	s_add_u32 s13, s38, 0x1200000
	v_lshlrev_b32_e32 v1, 2, v212
	v_lshrrev_b32_e32 v5, 3, v211
	s_addc_u32 s14, s39, 0
	v_lshrrev_b32_e32 v2, 5, v211
	v_and_b32_e32 v8, 0x7c, v1
	v_and_b32_e32 v1, 7, v212
	v_lshlrev_b32_e32 v3, 2, v5
	v_lshlrev_b32_e32 v12, 11, v5
	v_mov_b32_e32 v5, s26
	v_lshlrev_b32_e32 v10, 3, v1
	v_mul_u32_u24_e32 v1, 0x420, v1
	v_or_b32_e32 v14, 0x4000, v12
	v_or_b32_e32 v16, 0x8000, v12
	v_or_b32_e32 v18, 0xc000, v12
	s_cmp_lg_u64 s[2:3], 0
	v_mov_b32_e32 v9, v0
	v_mad_u32_u24 v5, v2, s33, v5
	v_add_u32_e32 v4, s27, v8
	v_add3_u32 v3, s27, v1, v3
	s_cselect_b64 s[0:1], -1, 0
	v_lshl_add_u64 v[6:7], s[2:3], 0, v[8:9]
	v_mov_b32_e32 v1, v2
	v_add3_u32 v5, v5, v8, 0
	v_lshlrev_b32_e32 v8, 1, v10
	v_lshlrev_b32_e32 v10, 1, v12
	v_lshlrev_b32_e32 v12, 1, v14
	v_lshlrev_b32_e32 v14, 1, v16
	v_lshlrev_b32_e32 v16, 1, v18
	s_branch .LBB0_611

; __device__ __forceinline__ unsigned cvt_pk_bf16(float lo, float hi) { unsigned r; asm volatile("v_cvt_pk_bf16_f32 %0, %1, %2" : "=v"(r) : "v"(lo), "v"(hi)); return r; }
; __global__ void __launch_bounds__(512) mega(Args a_byval) {
;     ...
;                 for (int i = gt; i < 2 * T * PLE / 8; i += NGT) { const f32x4 v0 = ((const f32x4*)p)[2 * i], v1 = ((const f32x4*)p)[2 * i + 1];
;                     u32x4 o; o.x = cvt_pk_bf16(v0[0], v0[1]); o.y = cvt_pk_bf16(v0[2], v0[3]); o.z = cvt_pk_bf16(v1[0], v1[1]); o.w = cvt_pk_bf16(v1[2], v1[3]); ((u32x4*)PB)[i] = o; }
.LBB0_618:
	v_cmp_gt_i32_e32 vcc, s91, v156
	s_and_saveexec_b64 s[0:1], vcc
	s_load_dwordx8 s[16:23], s[92:93], 0x0
	v_readlane_b32 s14, v254, 43
	v_readlane_b32 s15, v254, 44
	s_cbranch_execz .LBB0_621
	v_readlane_b32 s2, v254, 57
	v_ashrrev_i32_e32 v157, 31, v156
	v_readlane_b32 s3, v254, 58
	s_ashr_i32 s15, s14, 31
	v_lshlrev_b32_e32 v1, 1, v212
	v_readlane_b32 s8, v255, 5
	s_waitcnt lgkmcnt(0)
	v_lshl_add_u64 v[2:3], v[156:157], 4, s[2:3]
	s_lshl_b64 s[2:3], s[14:15], 4
	v_lshl_add_u32 v4, s94, 10, v1
	s_lshl_b32 s10, s8, 10
	s_cmpk_lg_i32 s8, 0x100
	s_cbranch_scc1 .Lpcv_generic
	v_ashrrev_i32_e32 v5, 31, v4
	v_lshl_add_u64 v[10:11], v[4:5], 4, s[18:19]
	global_load_dwordx4 v[20:23], v[10:11], off
	global_load_dwordx4 v[24:27], v[10:11], off offset:16
	v_add_u32_e32 v4, s10, v4
	v_ashrrev_i32_e32 v5, 31, v4
	v_lshl_add_u64 v[10:11], v[4:5], 4, s[18:19]
	global_load_dwordx4 v[28:31], v[10:11], off
	global_load_dwordx4 v[32:35], v[10:11], off offset:16
	v_add_u32_e32 v4, s10, v4
	v_ashrrev_i32_e32 v5, 31, v4
	v_lshl_add_u64 v[10:11], v[4:5], 4, s[18:19]
	global_load_dwordx4 v[36:39], v[10:11], off
	global_load_dwordx4 v[40:43], v[10:11], off offset:16
	v_add_u32_e32 v4, s10, v4
	v_ashrrev_i32_e32 v5, 31, v4
	v_lshl_add_u64 v[10:11], v[4:5], 4, s[18:19]
	global_load_dwordx4 v[44:47], v[10:11], off
	global_load_dwordx4 v[48:51], v[10:11], off offset:16
	v_add_u32_e32 v4, s10, v4
	s_waitcnt vmcnt(6)
	v_cvt_pk_bf16_f32 v6, v20, v21
	v_cvt_pk_bf16_f32 v7, v22, v23
	v_cvt_pk_bf16_f32 v8, v24, v25
	v_cvt_pk_bf16_f32 v9, v26, v27
	global_store_dwordx4 v[2:3], v[6:9], off
	s_nop 1
	v_lshl_add_u64 v[2:3], v[2:3], 0, s[2:3]
	s_waitcnt vmcnt(5)
	v_cvt_pk_bf16_f32 v14, v28, v29
	v_cvt_pk_bf16_f32 v15, v30, v31
	v_cvt_pk_bf16_f32 v16, v32, v33
	v_cvt_pk_bf16_f32 v17, v34, v35
	global_store_dwordx4 v[2:3], v[14:17], off
	s_nop 1
	v_lshl_add_u64 v[2:3], v[2:3], 0, s[2:3]
	s_waitcnt vmcnt(4)
	v_cvt_pk_bf16_f32 v6, v36, v37
	v_cvt_pk_bf16_f32 v7, v38, v39
	v_cvt_pk_bf16_f32 v8, v40, v41
	v_cvt_pk_bf16_f32 v9, v42, v43
	global_store_dwordx4 v[2:3], v[6:9], off
	s_nop 1
	v_lshl_add_u64 v[2:3], v[2:3], 0, s[2:3]
	s_waitcnt vmcnt(3)
	v_cvt_pk_bf16_f32 v14, v44, v45
	v_cvt_pk_bf16_f32 v15, v46, v47
	v_cvt_pk_bf16_f32 v16, v48, v49
	v_cvt_pk_bf16_f32 v17, v50, v51
	global_store_dwordx4 v[2:3], v[14:17], off
	s_nop 1
	v_lshl_add_u64 v[2:3], v[2:3], 0, s[2:3]
	s_branch .LBB0_621
.Lpcv_generic:
	s_mov_b64 s[8:9], 0
	v_mov_b32_e32 v1, v156
